# phase 3: pinned RWKV blocks (<256 on a 512-block grid) skip the second-queue fetch atomic after their job (queue is drained by blocks >=256); removes one atomic round trip from the P3 critical path
# speedup vs baseline: 1.0259x; 1.0040x over previous
.LBB0_469:
	s_barrier
	s_mov_b64 s[62:63], exec
	v_readlane_b32 s14, v237, 0
	v_readlane_b32 s15, v237, 1
	s_and_b64 s[14:15], s[62:63], s[14:15]
	s_mov_b64 exec, s[14:15]
	s_cbranch_execz .LBB0_473
	s_mov_b64 s[74:75], exec
	v_mbcnt_lo_u32_b32 v0, s74, 0
	v_mbcnt_hi_u32_b32 v0, s75, v0
	v_cmp_eq_u32_e32 vcc, 0, v0
	s_and_saveexec_b64 s[72:73], vcc
	s_cbranch_execz .LBB0_472
	s_bcnt1_i32_b64 s14, s[74:75]
	v_mov_b32_e32 v1, s14
	s_cmp_lt_u32 s33, 0x200
	s_cbranch_scc1 .Lmy_q2_atomic
	s_cmpk_ge_u32 s2, 0x100
	s_cbranch_scc1 .Lmy_q2_atomic
	v_mov_b32_e32 v1, 0x1000
	s_branch .Lmy_q2_join
.Lmy_q2_atomic:
	global_atomic_add v1, v113, v1, s[92:93] offset:4 sc0
.Lmy_q2_join:
.LBB0_472:
	s_or_b64 exec, exec, s[72:73]
	s_mov_b64 s[14:15], src_shared_base
	s_waitcnt vmcnt(0)
	v_readfirstlane_b32 s14, v1
	v_mov_b32_e32 v139, s15
	s_nop 0
	v_add_u32_e32 v0, s14, v0
	flat_store_dword v[138:139], v0 sc0 sc1
	s_waitcnt vmcnt(0)
